# plus SB tile loop: q fragments waited once in the unit prologue, per-step vmcnt waits in front of the QK MFMAs removed
# baseline (speedup 1.0000x reference)
; #define LOADT(i, kreg, vreg, creg) do { const int k0_ = KEY0(i); kreg = *(const u32x4*)(A.K + (size_t)(k0_ + lane) * A.ldkv + wid * 8); vreg = *(const u32x4*)(A.V + (size_t)(k0_ + lane) * A.ldkv + wid * 8); \
;         if (MODE == M_FOX) { if (tid < 64) creg = A.cf[k0_ + tid] * LOG2E; } } while (0)
; template <int MODE>
; __device__ __forceinline__ void attn_unit(LAS unsigned char* lds, const AttnArgs& A, int qb) {
;     int tid_ = threadIdx.x; asm volatile("" : "+v"(tid_)); const int tid = tid_, lane = tid & 63, wid = __builtin_amdgcn_readfirstlane(tid >> 6), r32 = lane & 31, hi = lane >> 5;
;     const int q0 = qb * 256, w0 = q0 + wid * 32, row = w0 + r32;
;     bf16x8 qr[4];
; #pragma unroll
;     for (int d0 = 0; d0 < 4; ++d0) qr[d0] = *(const bf16x8*)(A.Q + (size_t)row * A.ldq + d0 * 16 + hi * 8);
;     ...
;     f32x16 o0, o1;
; #pragma unroll
;     for (int r = 0; r < 16; ++r) { o0[r] = 0.f; o1[r] = 0.f; }
;     float m_run = -1e30f, l_run = 0.f, T = 0.f;
;     u32x4 k1 = (u32x4){0u, 0u, 0u, 0u}, v1 = k1, k2 = k1, v2 = k1, k3 = k1, v3 = k1; float c1 = 0.f, c2 = 0.f, c3 = 0.f;
;     ...
;     LOADT(0, k1, v1, c1); if (NT > 1) LOADT(1, k2, v2, c2); if (NT > 2) LOADT(2, k3, v3, c3);
;     STORET(0, k1, v1, c1);
;     __syncthreads();
.LBB0_1162:
	s_or_b64 exec, exec, s[6:7]
	v_mov_b32_e32 v0, s95
	s_waitcnt lgkmcnt(0)
	s_barrier
	ds_read_b32 v0, v0
	s_mov_b64 s[6:7], -1
	s_waitcnt lgkmcnt(0)
	s_barrier
	v_cmp_lt_i32_e32 vcc, s62, v0
	v_readfirstlane_b32 s0, v0
	s_cbranch_vccnz .LBB0_1157
	s_cmp_lt_i32 s0, 0
	s_cbranch_scc1 .LBB0_1156
	s_lshl_b32 s1, s0, 6
	s_and_b32 s1, s1, 0x1c0
	v_writelane_b32 v255, s1, 45
	s_lshl_b32 s1, s1, 1
	v_readlane_b32 s2, v255, 37
	s_add_u32 s2, s2, s1
	v_readlane_b32 s3, v255, 38
	s_addc_u32 s3, s3, 0
	v_readlane_b32 s4, v255, 39
	s_add_u32 s10, s4, s1
	v_readlane_b32 s4, v255, 40
	s_addc_u32 s11, s4, 0
	v_readlane_b32 s4, v255, 41
	s_add_u32 s12, s4, s1
	v_readlane_b32 s1, v255, 42
	s_addc_u32 s13, s1, 0
	s_lshl_b32 s0, s0, 5
	v_mov_b32_e32 v0, v216
	s_and_b32 s16, s0, 0x1fff00
	s_sub_i32 s6, 0x3f00, s16
	s_waitcnt vmcnt(9)
	v_and_b32_e32 v130, 63, v0
	v_readfirstlane_b32 s1, v0
	s_ashr_i32 s4, s1, 6
	v_or_b32_e32 v2, s6, v130
	v_lshlrev_b32_e32 v6, 11, v2
	s_lshl_b32 s0, s4, 3
	v_or_b32_e32 v2, 0x60000, v6
	v_mov_b32_e32 v3, v1
	s_ashr_i32 s1, s0, 31
	s_lshl_b32 s5, s4, 5
	v_lshl_add_u64 v[4:5], s[10:11], 0, v[2:3]
	s_lshl_b64 s[14:15], s[0:1], 1
	v_lshl_add_u64 v[2:3], s[12:13], 0, v[2:3]
	v_and_b32_e32 v12, 31, v0
	s_add_i32 s5, s5, s6
	v_lshl_add_u64 v[2:3], v[2:3], 0, s[14:15]
	s_waitcnt vmcnt(8)
	v_or_b32_e32 v126, s5, v12
	v_lshl_add_u64 v[4:5], v[4:5], 0, s[14:15]
	global_load_dwordx4 v[70:73], v[2:3], off
	v_mov_b32_e32 v3, v1
	v_ashrrev_i32_e32 v127, 31, v126
	v_or_b32_e32 v2, 0x40000, v6
	global_load_dwordx4 v[66:69], v[4:5], off
	v_mov_b32_e32 v5, v1
	v_bfe_u32 v13, v0, 5, 1
	v_or_b32_e32 v4, 0x20000, v6
	v_lshlrev_b64 v[6:7], 11, v[126:127]
	v_lshl_add_u64 v[8:9], s[10:11], 0, v[2:3]
	v_mov_b32_e32 v123, v1
	v_lshlrev_b32_e32 v122, 4, v13
	v_lshl_add_u64 v[2:3], s[12:13], 0, v[2:3]
	v_lshl_add_u64 v[10:11], s[12:13], 0, v[4:5]
	v_lshl_add_u64 v[4:5], s[10:11], 0, v[4:5]
	v_lshl_add_u64 v[6:7], s[2:3], 0, v[6:7]
	v_lshl_add_u64 v[8:9], v[8:9], 0, s[14:15]
	v_lshl_add_u64 v[2:3], v[2:3], 0, s[14:15]
	v_lshl_add_u64 v[10:11], v[10:11], 0, s[14:15]
	v_lshl_add_u64 v[4:5], v[4:5], 0, s[14:15]
	v_lshl_add_u64 v[6:7], v[6:7], 0, v[122:123]
	global_load_dwordx4 v[90:93], v[8:9], off
	global_load_dwordx4 v[94:97], v[2:3], off
	global_load_dwordx4 v[102:105], v[10:11], off
	global_load_dwordx4 v[98:101], v[4:5], off
	global_load_dwordx4 v[74:77], v[6:7], off
	global_load_dwordx4 v[78:81], v[6:7], off offset:32
	global_load_dwordx4 v[82:85], v[6:7], off offset:64
	global_load_dwordx4 v[86:89], v[6:7], off offset:96
	s_lshl_b32 s0, s4, 10
	s_lshl_b32 s1, s4, 7
	s_add_i32 s0, s0, 0
	v_lshlrev_b32_e32 v123, 4, v130
	v_lshlrev_b32_e32 v131, 1, v130
	s_mul_i32 s7, s4, 0xfffffb84
	s_add_i32 s85, s0, s1
	v_add_u32_e32 v133, s0, v123
	v_add_u32_e32 v134, s85, v131
	s_add_i32 s85, s85, s7
	s_mul_i32 s0, s4, 0x3fc
	s_lshr_b32 s76, s6, 6
	s_add_i32 s84, s85, s0
	s_add_i32 s2, s76, 4
	s_or_b32 s68, s76, 2
	s_or_b32 s69, s5, 31
	s_add_i32 s79, s84, s1
	v_lshlrev_b32_e32 v3, 1, v0
	v_lshrrev_b32_e32 v4, 1, v0
	s_add_u32 s90, s10, s14
	v_and_b32_e32 v2, 19, v0
	v_and_b32_e32 v3, 8, v3
	v_and_b32_e32 v4, 4, v4
	s_addc_u32 s91, s11, s15
	v_mov_b32_e32 v48, v1
	v_mov_b32_e32 v49, v1
	v_mov_b32_e32 v108, v1
	v_mov_b32_e32 v109, v1
	v_mul_u32_u24_e32 v132, 0x90, v12
	v_or3_b32 v2, v3, v2, v4
	s_add_u32 s88, s12, s14
	v_mov_b32_e32 v34, v1
	v_mov_b32_e32 v35, v1
	v_mov_b32_e32 v36, v1
	v_mov_b32_e32 v37, v1
	v_mov_b32_e32 v38, v1
	v_mov_b32_e32 v39, v1
	v_mov_b32_e32 v40, v1
	v_mov_b32_e32 v41, v1
	v_mov_b32_e32 v42, v1
	v_mov_b32_e32 v43, v1
	v_mov_b32_e32 v44, v1
	v_mov_b32_e32 v45, v1
	v_mov_b32_e32 v46, v1
	v_mov_b32_e32 v47, v1
	v_mov_b32_e32 v106, v1
	v_mov_b32_e32 v107, v1
	v_mov_b64_e32 v[116:117], v[108:109]
	v_mov_b64_e32 v[112:113], v[108:109]
	v_mov_b64_e32 v[120:121], v[108:109]
	v_mov_b64_e32 v[64:65], v[48:49]
	s_mov_b32 s3, 8
	v_lshlrev_b32_e32 v0, 3, v13
	v_lshlrev_b64 v[124:125], 10, v[126:127]
	v_lshl_add_u32 v127, v2, 4, 0
	v_lshlrev_b32_e32 v135, 10, v13
	v_cmp_gt_u32_e64 s[6:7], 32, v130
	s_mov_b32 s0, 0
	v_cmp_eq_u32_e64 s[8:9], 0, v130
	v_add3_u32 v136, 0, v132, v122
	s_addc_u32 s89, s13, s15
	s_sub_i32 s1, 0x3fff, s16
	v_mov_b32_e32 v129, 0
	s_mov_b64 s[12:13], 0
	v_mov_b64_e32 v[114:115], v[106:107]
	v_mov_b64_e32 v[110:111], v[106:107]
	v_mov_b64_e32 v[118:119], v[106:107]
	s_mov_b32 s16, 0
	v_mov_b64_e32 v[62:63], v[46:47]
	v_mov_b64_e32 v[60:61], v[44:45]
	v_mov_b64_e32 v[58:59], v[42:43]
	v_mov_b64_e32 v[56:57], v[40:41]
	v_mov_b64_e32 v[54:55], v[38:39]
	v_mov_b64_e32 v[52:53], v[36:37]
	v_mov_b64_e32 v[50:51], v[34:35]
	s_waitcnt vmcnt(0)
	ds_write_b128 v133, v[66:69]
	ds_write_b16 v134, v70 offset:8192
	ds_write_b16_d16_hi v134, v70 offset:8336
	ds_write_b16 v134, v71 offset:8480
	ds_write_b16_d16_hi v134, v71 offset:8624
	ds_write_b16 v134, v72 offset:8768
	ds_write_b16_d16_hi v134, v72 offset:8912
	ds_write_b16 v134, v73 offset:9056
	ds_write_b16_d16_hi v134, v73 offset:9200
	s_waitcnt lgkmcnt(0)
	s_barrier
	s_cmp_ge_u32 s0, s2
	s_mov_b64 s[10:11], -1
	s_cbranch_scc0 .LBB0_1166

; #define LAS __attribute__((address_space(3)))
; #define PVS(s, pk) do { const bf16x8 a0_ = *(const LAS bf16x8*)(vb + (s) * 32), a1_ = *(const LAS bf16x8*)(vb + 32 * VT_STRIDE + (s) * 32); \
;             o0 = __builtin_amdgcn_mfma_f32_32x32x16_bf16(a0_, pk, o0, 0, 0, 0); o1 = __builtin_amdgcn_mfma_f32_32x32x16_bf16(a1_, pk, o1, 0, 0, 0); } while (0)
; #define PVS(s, pk) do { const bf16x8 a0_ = *(const LAS bf16x8*)(vb + (s) * 32), a1_ = *(const LAS bf16x8*)(vb + 32 * VT_STRIDE + (s) * 32); \
;             o0 = __builtin_amdgcn_mfma_f32_32x32x16_bf16(a0_, pk, o0, 0, 0, 0); o1 = __builtin_amdgcn_mfma_f32_32x32x16_bf16(a1_, pk, o1, 0, 0, 0); } while (0)
; #define PVS(s, pk) do { const bf16x8 a0_ = *(const LAS bf16x8*)(vb + (s) * 32), a1_ = *(const LAS bf16x8*)(vb + 32 * VT_STRIDE + (s) * 32); \
;             o0 = __builtin_amdgcn_mfma_f32_32x32x16_bf16(a0_, pk, o0, 0, 0, 0); o1 = __builtin_amdgcn_mfma_f32_32x32x16_bf16(a1_, pk, o1, 0, 0, 0); } while (0)
; #define PVS(s, pk) do { const bf16x8 a0_ = *(const LAS bf16x8*)(vb + (s) * 32), a1_ = *(const LAS bf16x8*)(vb + 32 * VT_STRIDE + (s) * 32); \
;             o0 = __builtin_amdgcn_mfma_f32_32x32x16_bf16(a0_, pk, o0, 0, 0, 0); o1 = __builtin_amdgcn_mfma_f32_32x32x16_bf16(a1_, pk, o1, 0, 0, 0); } while (0)
; #define PVS(s, pk) do { const bf16x8 a0_ = *(const LAS bf16x8*)(vb + (s) * 32), a1_ = *(const LAS bf16x8*)(vb + 32 * VT_STRIDE + (s) * 32); \
;             o0 = __builtin_amdgcn_mfma_f32_32x32x16_bf16(a0_, pk, o0, 0, 0, 0); o1 = __builtin_amdgcn_mfma_f32_32x32x16_bf16(a1_, pk, o1, 0, 0, 0); } while (0)
; template <int MODE>
; __device__ __forceinline__ void attn_unit(LAS unsigned char* lds, const AttnArgs& A, int qb) {
;     ...
;             LAS unsigned char* kb = buf + kperm * 16 + hi * 1024;
; #pragma unroll
;             for (int d0 = 0; d0 < 4; ++d0) {
;                 const bf16x8 kf0 = *(const LAS bf16x8*)(kb + d0 * 2048), kf1 = *(const LAS bf16x8*)(kb + d0 * 2048 + 512);
;                 p0 = __builtin_amdgcn_mfma_f32_32x32x16_bf16(kf0, qr[d0], p0, 0, 0, 0);
;                 p1 = __builtin_amdgcn_mfma_f32_32x32x16_bf16(kf1, qr[d0], p1, 0, 0, 0);
;             }
;         if (prev_active) {
;             const LAS unsigned char* vb = lds + prevbuf + KB_BYTES + r32 * VT_STRIDE + hi * 16;
;     ...
;             PVS(0, pkP0); PVS(1, pkP1); PVS(2, pkP2); PVS(3, pkP3);
;     ...
;         }
.LBB0_1172:
	s_andn2_b64 vcc, exec, s[14:15]
	s_cbranch_vccnz .LBB0_1176
	v_add_u32_e32 v128, v127, v135
	s_nop 4
	ds_read_b128 v[2:5], v128
	ds_read_b128 v[138:141], v128 offset:2048
	s_and_b64 vcc, exec, s[10:11]
	s_waitcnt lgkmcnt(1)
	v_mfma_f32_32x32x16_bf16 v[18:33], v[2:5], v[74:77], 0
	ds_read_b128 v[2:5], v128 offset:512
	s_waitcnt lgkmcnt(1)
	v_mfma_f32_32x32x16_bf16 v[18:33], v[138:141], v[78:81], v[18:33]
	ds_read_b128 v[138:141], v128 offset:2560
	s_waitcnt lgkmcnt(1)
	v_mfma_f32_32x32x16_bf16 v[2:17], v[2:5], v[74:77], 0
	s_waitcnt lgkmcnt(0)
	v_mfma_f32_32x32x16_bf16 v[2:17], v[138:141], v[78:81], v[2:17]
	ds_read_b128 v[138:141], v128 offset:4096
	s_waitcnt lgkmcnt(0)
	v_mfma_f32_32x32x16_bf16 v[18:33], v[138:141], v[82:85], v[18:33]
	ds_read_b128 v[138:141], v128 offset:4608
	s_waitcnt lgkmcnt(0)
	v_mfma_f32_32x32x16_bf16 v[2:17], v[138:141], v[82:85], v[2:17]
	ds_read_b128 v[138:141], v128 offset:6144
	s_waitcnt lgkmcnt(0)
	v_mfma_f32_32x32x16_bf16 v[18:33], v[138:141], v[86:89], v[18:33]
	ds_read_b128 v[138:141], v128 offset:6656
	s_waitcnt lgkmcnt(0)
	v_mfma_f32_32x32x16_bf16 v[2:17], v[138:141], v[86:89], v[2:17]
	s_cbranch_vccnz .LBB0_1175
	v_add_u32_e32 v128, s16, v136
	ds_read_b128 v[138:141], v128 offset:8192
	s_waitcnt lgkmcnt(0)
	v_mfma_f32_32x32x16_bf16 v[50:65], v[138:141], v[118:121], v[50:65]
	ds_read_b128 v[138:141], v128 offset:12800
	s_waitcnt lgkmcnt(0)
	v_mfma_f32_32x32x16_bf16 v[34:49], v[138:141], v[118:121], v[34:49]
	ds_read_b128 v[118:121], v128 offset:8224
	s_waitcnt lgkmcnt(0)
	v_mfma_f32_32x32x16_bf16 v[50:65], v[118:121], v[110:113], v[50:65]
	ds_read_b128 v[118:121], v128 offset:12832
	s_waitcnt lgkmcnt(0)
	v_mfma_f32_32x32x16_bf16 v[34:49], v[118:121], v[110:113], v[34:49]
	ds_read_b128 v[110:113], v128 offset:8256
	s_waitcnt lgkmcnt(0)
	v_mfma_f32_32x32x16_bf16 v[50:65], v[110:113], v[114:117], v[50:65]
	ds_read_b128 v[110:113], v128 offset:12864
	s_waitcnt lgkmcnt(0)
	v_mfma_f32_32x32x16_bf16 v[34:49], v[110:113], v[114:117], v[34:49]
	ds_read_b128 v[110:113], v128 offset:8288
	s_waitcnt lgkmcnt(0)
	v_mfma_f32_32x32x16_bf16 v[50:65], v[110:113], v[106:109], v[50:65]
	ds_read_b128 v[110:113], v128 offset:12896
	s_waitcnt lgkmcnt(0)
	v_mfma_f32_32x32x16_bf16 v[34:49], v[110:113], v[106:109], v[34:49]

; #define LAS __attribute__((address_space(3)))
; #define PVS(s, pk) do { const bf16x8 a0_ = *(const LAS bf16x8*)(vb + (s) * 32), a1_ = *(const LAS bf16x8*)(vb + 32 * VT_STRIDE + (s) * 32); \
;             o0 = __builtin_amdgcn_mfma_f32_32x32x16_bf16(a0_, pk, o0, 0, 0, 0); o1 = __builtin_amdgcn_mfma_f32_32x32x16_bf16(a1_, pk, o1, 0, 0, 0); } while (0)
; #define PVS(s, pk) do { const bf16x8 a0_ = *(const LAS bf16x8*)(vb + (s) * 32), a1_ = *(const LAS bf16x8*)(vb + 32 * VT_STRIDE + (s) * 32); \
;             o0 = __builtin_amdgcn_mfma_f32_32x32x16_bf16(a0_, pk, o0, 0, 0, 0); o1 = __builtin_amdgcn_mfma_f32_32x32x16_bf16(a1_, pk, o1, 0, 0, 0); } while (0)
; #define PVS(s, pk) do { const bf16x8 a0_ = *(const LAS bf16x8*)(vb + (s) * 32), a1_ = *(const LAS bf16x8*)(vb + 32 * VT_STRIDE + (s) * 32); \
;             o0 = __builtin_amdgcn_mfma_f32_32x32x16_bf16(a0_, pk, o0, 0, 0, 0); o1 = __builtin_amdgcn_mfma_f32_32x32x16_bf16(a1_, pk, o1, 0, 0, 0); } while (0)
; #define PVS(s, pk) do { const bf16x8 a0_ = *(const LAS bf16x8*)(vb + (s) * 32), a1_ = *(const LAS bf16x8*)(vb + 32 * VT_STRIDE + (s) * 32); \
;             o0 = __builtin_amdgcn_mfma_f32_32x32x16_bf16(a0_, pk, o0, 0, 0, 0); o1 = __builtin_amdgcn_mfma_f32_32x32x16_bf16(a1_, pk, o1, 0, 0, 0); } while (0)
; #define PVS(s, pk) do { const bf16x8 a0_ = *(const LAS bf16x8*)(vb + (s) * 32), a1_ = *(const LAS bf16x8*)(vb + 32 * VT_STRIDE + (s) * 32); \
;             o0 = __builtin_amdgcn_mfma_f32_32x32x16_bf16(a0_, pk, o0, 0, 0, 0); o1 = __builtin_amdgcn_mfma_f32_32x32x16_bf16(a1_, pk, o1, 0, 0, 0); } while (0)
; template <int MODE>
; __device__ __forceinline__ void attn_unit(LAS unsigned char* lds, const AttnArgs& A, int qb) {
;     ...
;             LAS unsigned char* kb = buf + kperm * 16 + hi * 1024;
; #pragma unroll
;             for (int d0 = 0; d0 < 4; ++d0) {
;                 const bf16x8 kf0 = *(const LAS bf16x8*)(kb + d0 * 2048), kf1 = *(const LAS bf16x8*)(kb + d0 * 2048 + 512);
;                 p0 = __builtin_amdgcn_mfma_f32_32x32x16_bf16(kf0, qr[d0], p0, 0, 0, 0);
;                 p1 = __builtin_amdgcn_mfma_f32_32x32x16_bf16(kf1, qr[d0], p1, 0, 0, 0);
;             }
;         if (prev_active) {
;             const LAS unsigned char* vb = lds + prevbuf + KB_BYTES + r32 * VT_STRIDE + hi * 16;
;     ...
;             PVS(0, pkP0); PVS(1, pkP1); PVS(2, pkP2); PVS(3, pkP3);
;     ...
;         }
.LBB0_1189:
	s_andn2_b64 vcc, exec, s[12:13]
	s_cbranch_vccnz .LBB0_1195
	v_add_u32_e32 v128, v127, v135
	s_nop 4
	ds_read_b128 v[34:37], v128 offset:17664
	ds_read_b128 v[138:141], v128 offset:19712
	s_and_b64 vcc, exec, s[10:11]
	s_waitcnt lgkmcnt(1)
	v_mfma_f32_32x32x16_bf16 v[50:65], v[34:37], v[74:77], 0
	ds_read_b128 v[34:37], v128 offset:18176
	s_waitcnt lgkmcnt(1)
	v_mfma_f32_32x32x16_bf16 v[50:65], v[138:141], v[78:81], v[50:65]
	ds_read_b128 v[138:141], v128 offset:20224
	s_waitcnt lgkmcnt(1)
	v_mfma_f32_32x32x16_bf16 v[34:49], v[34:37], v[74:77], 0
	s_waitcnt lgkmcnt(0)
	v_mfma_f32_32x32x16_bf16 v[34:49], v[138:141], v[78:81], v[34:49]
	ds_read_b128 v[138:141], v128 offset:21760
	s_waitcnt lgkmcnt(0)
	v_mfma_f32_32x32x16_bf16 v[50:65], v[138:141], v[82:85], v[50:65]
	ds_read_b128 v[138:141], v128 offset:22272
	s_waitcnt lgkmcnt(0)
	v_mfma_f32_32x32x16_bf16 v[34:49], v[138:141], v[82:85], v[34:49]
	ds_read_b128 v[138:141], v128 offset:23808
	s_waitcnt lgkmcnt(0)
	v_mfma_f32_32x32x16_bf16 v[50:65], v[138:141], v[86:89], v[50:65]
	ds_read_b128 v[138:141], v128 offset:24320
	s_waitcnt lgkmcnt(0)
	v_mfma_f32_32x32x16_bf16 v[34:49], v[138:141], v[86:89], v[34:49]
	s_cbranch_vccnz .LBB0_1192
	ds_read_b128 v[138:141], v136 offset:8192
	s_waitcnt lgkmcnt(0)
	v_mfma_f32_32x32x16_bf16 v[2:17], v[138:141], v[118:121], v[2:17]
	ds_read_b128 v[138:141], v136 offset:12800
	s_waitcnt lgkmcnt(0)
	v_mfma_f32_32x32x16_bf16 v[18:33], v[138:141], v[118:121], v[18:33]
	ds_read_b128 v[118:121], v136 offset:8224
	s_waitcnt lgkmcnt(0)
	v_mfma_f32_32x32x16_bf16 v[2:17], v[118:121], v[110:113], v[2:17]
	ds_read_b128 v[118:121], v136 offset:12832
	s_waitcnt lgkmcnt(0)
	v_mfma_f32_32x32x16_bf16 v[18:33], v[118:121], v[110:113], v[18:33]
	ds_read_b128 v[110:113], v136 offset:8256
	s_waitcnt lgkmcnt(0)
	v_mfma_f32_32x32x16_bf16 v[2:17], v[110:113], v[114:117], v[2:17]
	ds_read_b128 v[110:113], v136 offset:12864
	s_waitcnt lgkmcnt(0)
	v_mfma_f32_32x32x16_bf16 v[18:33], v[110:113], v[114:117], v[18:33]
	ds_read_b128 v[110:113], v136 offset:8288
	s_waitcnt lgkmcnt(0)
	v_mfma_f32_32x32x16_bf16 v[2:17], v[110:113], v[106:109], v[2:17]
	ds_read_b128 v[110:113], v136 offset:12896
	s_waitcnt lgkmcnt(0)
	v_mfma_f32_32x32x16_bf16 v[18:33], v[110:113], v[106:109], v[18:33]

; #define LAS __attribute__((address_space(3)))
; #define PVS(s, pk) do { const bf16x8 a0_ = *(const LAS bf16x8*)(vb + (s) * 32), a1_ = *(const LAS bf16x8*)(vb + 32 * VT_STRIDE + (s) * 32); \
;             o0 = __builtin_amdgcn_mfma_f32_32x32x16_bf16(a0_, pk, o0, 0, 0, 0); o1 = __builtin_amdgcn_mfma_f32_32x32x16_bf16(a1_, pk, o1, 0, 0, 0); } while (0)
; #define PVS(s, pk) do { const bf16x8 a0_ = *(const LAS bf16x8*)(vb + (s) * 32), a1_ = *(const LAS bf16x8*)(vb + 32 * VT_STRIDE + (s) * 32); \
;             o0 = __builtin_amdgcn_mfma_f32_32x32x16_bf16(a0_, pk, o0, 0, 0, 0); o1 = __builtin_amdgcn_mfma_f32_32x32x16_bf16(a1_, pk, o1, 0, 0, 0); } while (0)
; #define PVS(s, pk) do { const bf16x8 a0_ = *(const LAS bf16x8*)(vb + (s) * 32), a1_ = *(const LAS bf16x8*)(vb + 32 * VT_STRIDE + (s) * 32); \
;             o0 = __builtin_amdgcn_mfma_f32_32x32x16_bf16(a0_, pk, o0, 0, 0, 0); o1 = __builtin_amdgcn_mfma_f32_32x32x16_bf16(a1_, pk, o1, 0, 0, 0); } while (0)
; #define PVS(s, pk) do { const bf16x8 a0_ = *(const LAS bf16x8*)(vb + (s) * 32), a1_ = *(const LAS bf16x8*)(vb + 32 * VT_STRIDE + (s) * 32); \
;             o0 = __builtin_amdgcn_mfma_f32_32x32x16_bf16(a0_, pk, o0, 0, 0, 0); o1 = __builtin_amdgcn_mfma_f32_32x32x16_bf16(a1_, pk, o1, 0, 0, 0); } while (0)
; #define PVS(s, pk) do { const bf16x8 a0_ = *(const LAS bf16x8*)(vb + (s) * 32), a1_ = *(const LAS bf16x8*)(vb + 32 * VT_STRIDE + (s) * 32); \
;             o0 = __builtin_amdgcn_mfma_f32_32x32x16_bf16(a0_, pk, o0, 0, 0, 0); o1 = __builtin_amdgcn_mfma_f32_32x32x16_bf16(a1_, pk, o1, 0, 0, 0); } while (0)
; template <int MODE>
; __device__ __forceinline__ void attn_unit(LAS unsigned char* lds, const AttnArgs& A, int qb) {
;     ...
;             LAS unsigned char* kb = buf + kperm * 16 + hi * 1024;
; #pragma unroll
;             for (int d0 = 0; d0 < 4; ++d0) {
;                 const bf16x8 kf0 = *(const LAS bf16x8*)(kb + d0 * 2048), kf1 = *(const LAS bf16x8*)(kb + d0 * 2048 + 512);
;                 p0 = __builtin_amdgcn_mfma_f32_32x32x16_bf16(kf0, qr[d0], p0, 0, 0, 0);
;                 p1 = __builtin_amdgcn_mfma_f32_32x32x16_bf16(kf1, qr[d0], p1, 0, 0, 0);
;             }
;         if (prev_active) {
;             const LAS unsigned char* vb = lds + prevbuf + KB_BYTES + r32 * VT_STRIDE + hi * 16;
;     ...
;             PVS(0, pkP0); PVS(1, pkP1); PVS(2, pkP2); PVS(3, pkP3);
;     ...
;         }
.LBB0_1207:
	s_andn2_b64 vcc, exec, s[12:13]
	s_cbranch_vccnz .LBB0_1212
	v_add_u32_e32 v128, v127, v135
	s_nop 4
	ds_read_b128 v[34:37], v128 offset:35328
	ds_read_b128 v[138:141], v128 offset:37376
	s_and_b64 vcc, exec, s[10:11]
	s_waitcnt lgkmcnt(1)
	v_mfma_f32_32x32x16_bf16 v[50:65], v[34:37], v[74:77], 0
	ds_read_b128 v[34:37], v128 offset:35840
	s_waitcnt lgkmcnt(1)
	v_mfma_f32_32x32x16_bf16 v[50:65], v[138:141], v[78:81], v[50:65]
	ds_read_b128 v[138:141], v128 offset:37888
	s_waitcnt lgkmcnt(1)
	v_mfma_f32_32x32x16_bf16 v[34:49], v[34:37], v[74:77], 0
	s_waitcnt lgkmcnt(0)
	v_mfma_f32_32x32x16_bf16 v[34:49], v[138:141], v[78:81], v[34:49]
	ds_read_b128 v[138:141], v128 offset:39424
	s_waitcnt lgkmcnt(0)
	v_mfma_f32_32x32x16_bf16 v[50:65], v[138:141], v[82:85], v[50:65]
	ds_read_b128 v[138:141], v128 offset:39936
	s_waitcnt lgkmcnt(0)
	v_mfma_f32_32x32x16_bf16 v[34:49], v[138:141], v[82:85], v[34:49]
	ds_read_b128 v[138:141], v128 offset:41472
	s_waitcnt lgkmcnt(0)
	v_mfma_f32_32x32x16_bf16 v[50:65], v[138:141], v[86:89], v[50:65]
	ds_read_b128 v[138:141], v128 offset:41984
	s_waitcnt lgkmcnt(0)
	v_mfma_f32_32x32x16_bf16 v[34:49], v[138:141], v[86:89], v[34:49]
	s_cbranch_vccnz .LBB0_1210
	v_add_u32_e32 v128, s16, v136
	ds_read_b128 v[138:141], v128 offset:8192
	s_waitcnt lgkmcnt(0)
	v_mfma_f32_32x32x16_bf16 v[2:17], v[138:141], v[118:121], v[2:17]
	ds_read_b128 v[138:141], v128 offset:12800
	s_waitcnt lgkmcnt(0)
	v_mfma_f32_32x32x16_bf16 v[18:33], v[138:141], v[118:121], v[18:33]
	ds_read_b128 v[118:121], v128 offset:8224
	s_waitcnt lgkmcnt(0)
	v_mfma_f32_32x32x16_bf16 v[2:17], v[118:121], v[110:113], v[2:17]
	ds_read_b128 v[118:121], v128 offset:12832
	s_waitcnt lgkmcnt(0)
	v_mfma_f32_32x32x16_bf16 v[18:33], v[118:121], v[110:113], v[18:33]
	ds_read_b128 v[110:113], v128 offset:8256
	s_waitcnt lgkmcnt(0)
	v_mfma_f32_32x32x16_bf16 v[2:17], v[110:113], v[114:117], v[2:17]
	ds_read_b128 v[110:113], v128 offset:12864
	s_waitcnt lgkmcnt(0)
	v_mfma_f32_32x32x16_bf16 v[18:33], v[110:113], v[114:117], v[18:33]
	ds_read_b128 v[110:113], v128 offset:8288
	s_waitcnt lgkmcnt(0)
	v_mfma_f32_32x32x16_bf16 v[2:17], v[110:113], v[106:109], v[2:17]
	ds_read_b128 v[110:113], v128 offset:12896
	s_waitcnt lgkmcnt(0)
	v_mfma_f32_32x32x16_bf16 v[18:33], v[110:113], v[106:109], v[18:33]
